# GEMM-phase prologue de-serialised: second K-tile's 6 LDS-DMA loads issued before the first wait (vmcnt 2->8)
# baseline (speedup 1.0000x reference)
; #define PG8_STAGE(bufoff, gbase, voff) do { _Pragma("unroll") for (int _i = 0; _i < 2; ++_i) \
;         __builtin_amdgcn_global_load_lds((const unsigned*)((const char*)(gbase) + (voff)[_i]), (PG8_LAS unsigned*)(lds + (bufoff) + ldsw + _i * 8192), 16, 0, 0); } while (0)
; #define PG8_WAIT_V(n) asm volatile("s_waitcnt vmcnt(" #n ")" ::: "memory")
; #define PG8_BAR __builtin_amdgcn_s_barrier()
; template <class Epi, class Sched, bool ALIGN_EPI = false, bool SP2 = false>
; __device__ __forceinline__ void gemm_phase(PG8_LAS unsigned char* lds, const Gemm g, const Sched& S, const Epi& E) {
;     ...
;         PG8_STAGE(PG8_SB(0, 0), cB, voffB); PG8_STAGE(PG8_SB(0, 1), cB + hstep, voffB); PG8_STAGE(PG8_SA(0, 0), cA, voffA); PG8_STAGE(PG8_SA(0, 1), cA + hstep, voffA);
;         if (wr == 1) PG8_BAR;
;         PG8_WAIT_V(2); PG8_BAR;
;         PG8_STAGE(PG8_SB(1, 0), cB + kstep, voffB); PG8_STAGE(PG8_SA(1, 0), cA + kstep, voffA); PG8_STAGE(PG8_SB(1, 1), cB + hstep + kstep, voffB);
;         PG8_WAIT_V(6); PG8_BAR;
.LBB0_216:
	s_add_u32 s14, s6, 0x1a600000
	s_addc_u32 s15, s7, 0
	s_add_u32 s16, s16, 0x1bd14500
	s_addc_u32 s17, s17, 0
	s_add_i32 m0, s47, 0x18000
	v_lshl_add_u64 v[10:11], v[10:11], 0, s[52:53]
	global_load_lds_dwordx4 v[10:11], off
	v_lshl_add_u64 v[6:7], v[6:7], 0, s[52:53]
	s_add_i32 m0, s47, 0x1a000
	s_add_i32 s67, s47, 0x8000
	global_load_lds_dwordx4 v[6:7], off
	v_lshl_add_u64 v[6:7], v[8:9], 0, s[52:53]
	s_mov_b32 m0, s67
	s_add_i32 s68, s47, 0xa000
	global_load_lds_dwordx4 v[6:7], off
	v_lshl_add_u64 v[6:7], v[12:13], 0, s[52:53]
	s_mov_b32 m0, s68
	v_lshl_add_u64 v[4:5], v[4:5], 0, s[52:53]
	global_load_lds_dwordx4 v[6:7], off
	s_add_i32 m0, s47, 0x1c000
	v_lshl_add_u64 v[2:3], v[2:3], 0, s[52:53]
	global_load_lds_dwordx4 v[4:5], off
	s_add_i32 m0, s47, 0x1e000
	v_bfe_u32 v159, v14, 4, 2
	global_load_lds_dwordx4 v[2:3], off
	s_waitcnt vmcnt(8)
	s_barrier
	s_lshr_b32 s5, s5, 26
	v_and_b32_e32 v161, 15, v14
	s_add_i32 s5, s4, s5
	v_lshlrev_b32_e32 v2, 4, v159
	v_lshlrev_b32_e32 v3, 2, v14
	s_ashr_i32 s69, s5, 6
	v_lshl_or_b32 v2, v161, 6, v2
	s_lshl_b32 s5, s19, 13
	v_and_b32_e32 v3, 32, v3
	v_bitop3_b32 v4, v2, s5, v3 bitop3:0xde
	s_lshl_b32 s5, s21, 5
	s_and_b32 s5, s5, 0x60
	s_sext_i32_i16 s81, s18
	s_lshl_b32 s70, s19, 6
	s_lshl_b32 s18, s5, 7
	v_bitop3_b32 v163, v2, s18, v3 bitop3:0xde
	s_cmp_gt_i32 s4, 63
	v_add_u32_e32 v2, v17, v15
	s_cselect_b64 s[18:19], -1, 0
	s_add_i32 s71, s69, -2
	v_add_lshl_u32 v2, v2, v16, 1
	v_mov_b32_e32 v3, v1
	s_waitcnt vmcnt(6)
	s_cmpk_lt_u32 s20, 0x100
	v_lshl_add_u64 v[136:137], s[8:9], 0, v[2:3]
	v_add_u32_e32 v2, v20, v18
	s_cselect_b64 s[20:21], -1, 0
	s_add_u32 s22, s6, 0x1a708100
	v_add_lshl_u32 v2, v2, v19, 1
	s_addc_u32 s23, s7, 0
	s_ashr_i32 s73, s2, 31
	v_lshl_add_u64 v[138:139], s[8:9], 0, v[2:3]
	s_mov_b32 s75, 0
	v_add_u32_e32 v165, 0, v4
	s_lshl_b32 s48, s5, 1
	s_barrier
	s_branch .LBB0_219

; #define PG8_STAGE(bufoff, gbase, voff) do { _Pragma("unroll") for (int _i = 0; _i < 2; ++_i) \
;         __builtin_amdgcn_global_load_lds((const unsigned*)((const char*)(gbase) + (voff)[_i]), (PG8_LAS unsigned*)(lds + (bufoff) + ldsw + _i * 8192), 16, 0, 0); } while (0)
; #define PG8_WAIT_V(n) asm volatile("s_waitcnt vmcnt(" #n ")" ::: "memory")
; #define PG8_BAR __builtin_amdgcn_s_barrier()
; template <class Epi, class Sched, bool ALIGN_EPI = false, bool SP2 = false>
; __device__ __forceinline__ void gemm_phase(PG8_LAS unsigned char* lds, const Gemm g, const Sched& S, const Epi& E) {
;     ...
;         PG8_STAGE(PG8_SB(0, 0), cB, voffB); PG8_STAGE(PG8_SB(0, 1), cB + hstep, voffB); PG8_STAGE(PG8_SA(0, 0), cA, voffA); PG8_STAGE(PG8_SA(0, 1), cA + hstep, voffA);
;         if (wr == 1) PG8_BAR;
;         PG8_WAIT_V(2); PG8_BAR;
;         PG8_STAGE(PG8_SB(1, 0), cB + kstep, voffB); PG8_STAGE(PG8_SA(1, 0), cA + kstep, voffA); PG8_STAGE(PG8_SB(1, 1), cB + hstep + kstep, voffB);
;         PG8_WAIT_V(6); PG8_BAR;
.LBB0_327:
	s_add_u32 s14, s14, 0x14300000
	s_addc_u32 s15, s15, 0
	s_add_u32 s16, s16, 0x18500000
	s_addc_u32 s17, s17, 0
	s_add_u32 s66, s18, 0x1a600000
	s_addc_u32 s67, s19, 0
	s_add_i32 m0, s56, 0x18000
	v_lshl_add_u64 v[2:3], v[2:3], 0, s[52:53]
	global_load_lds_dwordx4 v[2:3], off
	v_lshl_add_u64 v[2:3], v[4:5], 0, s[52:53]
	s_add_i32 m0, s56, 0x1a000
	s_add_i32 s68, s56, 0x8000
	global_load_lds_dwordx4 v[2:3], off
	v_lshl_add_u64 v[2:3], v[10:11], 0, s[52:53]
	s_mov_b32 m0, s68
	s_add_i32 s69, s56, 0xa000
	global_load_lds_dwordx4 v[2:3], off
	v_lshl_add_u64 v[2:3], v[12:13], 0, s[52:53]
	s_mov_b32 m0, s69
	v_bfe_u32 v189, v14, 4, 2
	global_load_lds_dwordx4 v[2:3], off
	s_add_i32 m0, s56, 0x1c000
	v_lshl_add_u64 v[2:3], v[6:7], 0, s[52:53]
	global_load_lds_dwordx4 v[2:3], off
	v_lshl_add_u64 v[2:3], v[8:9], 0, s[52:53]
	s_add_i32 m0, s56, 0x1e000
	s_lshr_b32 s7, s7, 26
	global_load_lds_dwordx4 v[2:3], off
	s_waitcnt vmcnt(8)
	s_barrier
	v_and_b32_e32 v233, 15, v14
	s_add_i32 s7, s6, s7
	v_lshlrev_b32_e32 v2, 4, v189
	v_lshlrev_b32_e32 v3, 2, v14
	s_and_b32 s70, s20, 3
	s_ashr_i32 s71, s7, 6
	v_lshl_or_b32 v2, v233, 6, v2
	s_lshl_b32 s7, s21, 13
	v_and_b32_e32 v3, 32, v3
	s_lshl_b32 s73, s21, 6
	v_bitop3_b32 v4, v2, s7, v3 bitop3:0xde
	s_lshl_b32 s48, s70, 5
	s_lshl_b32 s7, s70, 12
	s_cmp_gt_i32 s6, 63
	v_bitop3_b32 v234, v2, s7, v3 bitop3:0xde
	s_cselect_b64 s[18:19], -1, 0
	s_add_i32 s75, s71, -2
	v_add_u32_e32 v2, v17, v15
	s_cmpk_lt_u32 s22, 0x100
	v_add_lshl_u32 v2, v2, v16, 1
	v_mov_b32_e32 v3, v1
	s_waitcnt vmcnt(6)
	s_cselect_b64 s[20:21], -1, 0
	s_ashr_i32 s78, s24, 31
	s_ashr_i32 s79, s2, 31
	s_lshl_b32 s6, s70, 7
	v_lshl_add_u64 v[136:137], s[8:9], 0, v[2:3]
	v_add_u32_e32 v2, v20, v18
	s_add_u32 s81, s4, s6
	v_add_lshl_u32 v2, v2, v19, 1
	s_addc_u32 s82, s5, 0
	v_lshl_add_u64 v[138:139], s[8:9], 0, v[2:3]
	s_mov_b32 s83, 0
	v_add_u32_e32 v235, 0, v4
	s_barrier
	s_branch .LBB0_330

; #define PG8_STAGE(bufoff, gbase, voff) do { _Pragma("unroll") for (int _i = 0; _i < 2; ++_i) \
;         __builtin_amdgcn_global_load_lds((const unsigned*)((const char*)(gbase) + (voff)[_i]), (PG8_LAS unsigned*)(lds + (bufoff) + ldsw + _i * 8192), 16, 0, 0); } while (0)
; #define PG8_WAIT_V(n) asm volatile("s_waitcnt vmcnt(" #n ")" ::: "memory")
; #define PG8_BAR __builtin_amdgcn_s_barrier()
; template <class Epi, class Sched, bool ALIGN_EPI = false, bool SP2 = false>
; __device__ __forceinline__ void gemm_phase(PG8_LAS unsigned char* lds, const Gemm g, const Sched& S, const Epi& E) {
;     ...
;         PG8_STAGE(PG8_SB(0, 0), cB, voffB); PG8_STAGE(PG8_SB(0, 1), cB + hstep, voffB); PG8_STAGE(PG8_SA(0, 0), cA, voffA); PG8_STAGE(PG8_SA(0, 1), cA + hstep, voffA);
;         if (wr == 1) PG8_BAR;
;         PG8_WAIT_V(2); PG8_BAR;
;         PG8_STAGE(PG8_SB(1, 0), cB + kstep, voffB); PG8_STAGE(PG8_SA(1, 0), cA + kstep, voffA); PG8_STAGE(PG8_SB(1, 1), cB + hstep + kstep, voffB);
;         PG8_WAIT_V(6); PG8_BAR;
.LBB0_369:
	s_add_u32 s14, s4, 0x1a714500
	s_addc_u32 s15, s5, 0
	s_add_i32 m0, s13, 0x18000
	v_lshl_add_u64 v[2:3], v[2:3], 0, s[52:53]
	global_load_lds_dwordx4 v[2:3], off
	v_lshl_add_u64 v[2:3], v[4:5], 0, s[52:53]
	s_add_i32 m0, s13, 0x1a000
	s_add_i32 s66, s13, 0x8000
	global_load_lds_dwordx4 v[2:3], off
	v_lshl_add_u64 v[2:3], v[10:11], 0, s[52:53]
	s_mov_b32 m0, s66
	s_add_i32 s67, s13, 0xa000
	global_load_lds_dwordx4 v[2:3], off
	v_lshl_add_u64 v[2:3], v[12:13], 0, s[52:53]
	s_mov_b32 m0, s67
	s_ashr_i32 s4, s16, 31
	global_load_lds_dwordx4 v[2:3], off
	s_add_i32 m0, s13, 0x1c000
	v_lshl_add_u64 v[2:3], v[6:7], 0, s[52:53]
	global_load_lds_dwordx4 v[2:3], off
	v_lshl_add_u64 v[2:3], v[8:9], 0, s[52:53]
	s_add_i32 m0, s13, 0x1e000
	v_bfe_u32 v76, v14, 4, 2
	global_load_lds_dwordx4 v[2:3], off
	s_waitcnt vmcnt(8)
	s_barrier
	s_lshr_b32 s4, s4, 26
	v_and_b32_e32 v77, 15, v14
	s_add_i32 s4, s16, s4
	v_lshlrev_b32_e32 v2, 4, v76
	v_lshlrev_b32_e32 v3, 2, v14
	s_ashr_i32 s68, s4, 6
	v_lshl_or_b32 v2, v77, 6, v2
	s_lshl_b32 s4, s19, 13
	v_and_b32_e32 v3, 32, v3
	v_bitop3_b32 v4, v2, s4, v3 bitop3:0xde
	s_lshl_b32 s4, s17, 5
	s_and_b32 s4, s4, 0x60
	s_lshl_b32 s5, s4, 7
	s_lshl_b32 s69, s19, 6
	v_bitop3_b32 v78, v2, s5, v3 bitop3:0xde
	v_add_u32_e32 v2, v20, v18
	s_cmp_gt_i32 s16, 63
	v_add_lshl_u32 v2, v2, v19, 1
	v_mov_b32_e32 v3, v1
	s_waitcnt vmcnt(6)
	s_cselect_b64 s[16:17], -1, 0
	s_add_i32 s70, s68, -2
	v_lshl_add_u64 v[72:73], s[6:7], 0, v[2:3]
	v_add_u32_e32 v2, v17, v15
	s_cmpk_lt_u32 s18, 0x100
	v_add_lshl_u32 v2, v2, v16, 1
	s_cselect_b64 s[18:19], -1, 0
	s_ashr_i32 s71, s69, 31
	v_lshl_add_u64 v[74:75], s[6:7], 0, v[2:3]
	s_mov_b32 s73, 0
	v_add_u32_e32 v79, 0, v4
	s_lshl_b32 s48, s4, 2
	s_barrier
	s_branch .LBB0_372

; #define PG8_STAGE(bufoff, gbase, voff) do { _Pragma("unroll") for (int _i = 0; _i < 2; ++_i) \
;         __builtin_amdgcn_global_load_lds((const unsigned*)((const char*)(gbase) + (voff)[_i]), (PG8_LAS unsigned*)(lds + (bufoff) + ldsw + _i * 8192), 16, 0, 0); } while (0)
; #define PG8_WAIT_V(n) asm volatile("s_waitcnt vmcnt(" #n ")" ::: "memory")
; #define PG8_BAR __builtin_amdgcn_s_barrier()
; template <class Epi, class Sched, bool ALIGN_EPI = false, bool SP2 = false>
; __device__ __forceinline__ void gemm_phase(PG8_LAS unsigned char* lds, const Gemm g, const Sched& S, const Epi& E) {
;     ...
;         PG8_STAGE(PG8_SB(0, 0), cB, voffB); PG8_STAGE(PG8_SB(0, 1), cB + hstep, voffB); PG8_STAGE(PG8_SA(0, 0), cA, voffA); PG8_STAGE(PG8_SA(0, 1), cA + hstep, voffA);
;         if (wr == 1) PG8_BAR;
;         PG8_WAIT_V(2); PG8_BAR;
;         PG8_STAGE(PG8_SB(1, 0), cB + kstep, voffB); PG8_STAGE(PG8_SA(1, 0), cA + kstep, voffA); PG8_STAGE(PG8_SB(1, 1), cB + hstep + kstep, voffB);
;         PG8_WAIT_V(6); PG8_BAR;
.LBB0_507:
	s_add_u32 s18, s6, 0x1a600000
	s_addc_u32 s19, s7, 0
	s_add_u32 s85, s54, 0x217d4500
	s_addc_u32 s86, s55, 0
	s_add_u32 s87, s30, 0x238d4500
	s_addc_u32 s90, s31, 0
	s_add_u32 s20, s20, 0x259d4500
	s_addc_u32 s21, s21, 0
	s_add_u32 s22, s22, 0x27ad4500
	s_addc_u32 s23, s23, 0
	s_add_u32 s28, s28, 0x29bd4500
	s_addc_u32 s29, s29, 0
	s_add_i32 m0, s79, 0x18000
	v_lshl_add_u64 v[2:3], v[2:3], 0, s[52:53]
	global_load_lds_dwordx4 v[2:3], off
	v_lshl_add_u64 v[2:3], v[4:5], 0, s[52:53]
	s_add_i32 m0, s79, 0x1a000
	s_add_i32 s91, s79, 0x8000
	global_load_lds_dwordx4 v[2:3], off
	v_lshl_add_u64 v[2:3], v[10:11], 0, s[52:53]
	s_mov_b32 m0, s91
	s_add_i32 s35, s79, 0xa000
	global_load_lds_dwordx4 v[2:3], off
	v_lshl_add_u64 v[2:3], v[12:13], 0, s[52:53]
	s_mov_b32 m0, s35
	v_bfe_u32 v189, v14, 4, 2
	global_load_lds_dwordx4 v[2:3], off
	s_add_i32 m0, s79, 0x1c000
	v_lshl_add_u64 v[2:3], v[6:7], 0, s[52:53]
	global_load_lds_dwordx4 v[2:3], off
	v_lshl_add_u64 v[2:3], v[8:9], 0, s[52:53]
	s_add_i32 m0, s79, 0x1e000
	v_and_b32_e32 v194, 15, v14
	global_load_lds_dwordx4 v[2:3], off
	s_waitcnt vmcnt(8)
	s_barrier
	v_lshlrev_b32_e32 v2, 4, v189
	v_lshlrev_b32_e32 v3, 2, v14
	s_lshr_b32 s2, s5, 26
	v_lshl_or_b32 v2, v194, 6, v2
	s_lshl_b32 s5, s45, 13
	v_and_b32_e32 v3, 32, v3
	v_bitop3_b32 v4, v2, s5, v3 bitop3:0xde
	s_lshl_b32 s5, s57, 5
	s_add_i32 s2, s4, s2
	s_and_b32 s66, s5, 0x60
	s_ashr_i32 s2, s2, 6
	s_lshl_b32 s56, s45, 6
	s_lshl_b32 s5, s66, 7
	s_cmp_gt_i32 s4, 63
	v_bitop3_b32 v195, v2, s5, v3 bitop3:0xde
	s_cselect_b64 s[30:31], -1, 0
	s_add_i32 s67, s2, -2
	v_add_u32_e32 v2, v17, v15
	s_cmpk_lt_u32 s27, 0x100
	v_add_lshl_u32 v2, v2, v16, 1
	v_mov_b32_e32 v3, v1
	s_waitcnt vmcnt(6)
	s_cselect_b64 s[92:93], -1, 0
	s_ashr_i32 s27, s24, 31
	s_ashr_i32 s75, s37, 31
	v_lshl_add_u64 v[136:137], s[12:13], 0, v[2:3]
	v_add_u32_e32 v2, v20, v18
	s_add_u32 s94, s6, 0x1a708100
	v_add_lshl_u32 v2, v2, v19, 1
	s_addc_u32 s95, s7, 0
	v_lshl_add_u64 v[138:139], s[12:13], 0, v[2:3]
	s_mov_b32 s57, 0
	v_add_u32_e32 v196, 0, v4
	s_barrier
	s_branch .LBB0_510

; #define PG8_STAGE(bufoff, gbase, voff) do { _Pragma("unroll") for (int _i = 0; _i < 2; ++_i) \
;         __builtin_amdgcn_global_load_lds((const unsigned*)((const char*)(gbase) + (voff)[_i]), (PG8_LAS unsigned*)(lds + (bufoff) + ldsw + _i * 8192), 16, 0, 0); } while (0)
; #define PG8_WAIT_V(n) asm volatile("s_waitcnt vmcnt(" #n ")" ::: "memory")
; #define PG8_BAR __builtin_amdgcn_s_barrier()
; template <class Epi, class Sched, bool ALIGN_EPI = false, bool SP2 = false>
; __device__ __forceinline__ void gemm_phase(PG8_LAS unsigned char* lds, const Gemm g, const Sched& S, const Epi& E) {
;     ...
;         PG8_STAGE(PG8_SB(0, 0), cB, voffB); PG8_STAGE(PG8_SB(0, 1), cB + hstep, voffB); PG8_STAGE(PG8_SA(0, 0), cA, voffA); PG8_STAGE(PG8_SA(0, 1), cA + hstep, voffA);
;         if (wr == 1) PG8_BAR;
;         PG8_WAIT_V(2); PG8_BAR;
;         PG8_STAGE(PG8_SB(1, 0), cB + kstep, voffB); PG8_STAGE(PG8_SA(1, 0), cA + kstep, voffA); PG8_STAGE(PG8_SB(1, 1), cB + hstep + kstep, voffB);
;         PG8_WAIT_V(6); PG8_BAR;
.LBB0_1036:
	s_add_u32 s14, s14, 0x14300000
	s_addc_u32 s15, s15, 0
	s_add_u32 s16, s16, 0x18500000
	s_addc_u32 s17, s17, 0
	s_add_u32 s58, s18, 0x1a600000
	s_addc_u32 s59, s19, 0
	s_add_i32 m0, s45, 0x18000
	v_lshl_add_u64 v[2:3], v[2:3], 0, s[52:53]
	global_load_lds_dwordx4 v[2:3], off
	v_lshl_add_u64 v[2:3], v[4:5], 0, s[52:53]
	s_add_i32 m0, s45, 0x1a000
	s_add_i32 s66, s45, 0x8000
	global_load_lds_dwordx4 v[2:3], off
	v_lshl_add_u64 v[2:3], v[10:11], 0, s[52:53]
	s_mov_b32 m0, s66
	s_add_i32 s67, s45, 0xa000
	global_load_lds_dwordx4 v[2:3], off
	v_lshl_add_u64 v[2:3], v[12:13], 0, s[52:53]
	s_mov_b32 m0, s67
	v_bfe_u32 v189, v14, 4, 2
	global_load_lds_dwordx4 v[2:3], off
	s_add_i32 m0, s45, 0x1c000
	v_lshl_add_u64 v[2:3], v[6:7], 0, s[52:53]
	global_load_lds_dwordx4 v[2:3], off
	v_lshl_add_u64 v[2:3], v[8:9], 0, s[52:53]
	s_add_i32 m0, s45, 0x1e000
	s_lshr_b32 s7, s7, 26
	global_load_lds_dwordx4 v[2:3], off
	s_waitcnt vmcnt(8)
	s_barrier
	v_and_b32_e32 v216, 15, v14
	s_add_i32 s7, s6, s7
	v_lshlrev_b32_e32 v2, 4, v189
	v_lshlrev_b32_e32 v3, 2, v14
	s_and_b32 s68, s20, 3
	s_ashr_i32 s69, s7, 6
	v_lshl_or_b32 v2, v216, 6, v2
	s_lshl_b32 s7, s21, 13
	v_and_b32_e32 v3, 32, v3
	s_lshl_b32 s70, s21, 6
	v_bitop3_b32 v4, v2, s7, v3 bitop3:0xde
	s_lshl_b32 s48, s68, 5
	s_lshl_b32 s7, s68, 12
	s_cmp_gt_i32 s6, 63
	s_cselect_b64 s[18:19], -1, 0
	s_add_i32 s71, s69, -2
	s_cmpk_lt_u32 s22, 0x100
	v_bitop3_b32 v217, v2, s7, v3 bitop3:0xde
	s_cselect_b64 s[20:21], -1, 0
	s_ashr_i32 s73, s24, 31
	s_ashr_i32 s75, s2, 31
	s_lshl_b32 s6, s68, 7
	v_add_u32_e32 v2, v17, v15
	s_add_u32 s4, s4, s6
	v_add_lshl_u32 v2, v2, v16, 1
	v_mov_b32_e32 v3, v1
	s_waitcnt vmcnt(6)
	s_addc_u32 s5, s5, 0
	v_lshl_add_u64 v[200:201], s[8:9], 0, v[2:3]
	v_add_u32_e32 v2, v20, v18
	s_add_u32 s78, s4, 0x14300000
	v_add_lshl_u32 v2, v2, v19, 1
	s_addc_u32 s79, s5, 0
	v_lshl_add_u64 v[202:203], s[8:9], 0, v[2:3]
	s_mov_b32 s81, 0
	v_add_u32_e32 v233, 0, v4
	s_barrier
	s_branch .LBB0_1039

; #define PG8_STAGE(bufoff, gbase, voff) do { _Pragma("unroll") for (int _i = 0; _i < 2; ++_i) \
;         __builtin_amdgcn_global_load_lds((const unsigned*)((const char*)(gbase) + (voff)[_i]), (PG8_LAS unsigned*)(lds + (bufoff) + ldsw + _i * 8192), 16, 0, 0); } while (0)
; #define PG8_WAIT_V(n) asm volatile("s_waitcnt vmcnt(" #n ")" ::: "memory")
; #define PG8_BAR __builtin_amdgcn_s_barrier()
; template <class Epi, class Sched, bool ALIGN_EPI = false, bool SP2 = false>
; __device__ __forceinline__ void gemm_phase(PG8_LAS unsigned char* lds, const Gemm g, const Sched& S, const Epi& E) {
;     ...
;         PG8_STAGE(PG8_SB(0, 0), cB, voffB); PG8_STAGE(PG8_SB(0, 1), cB + hstep, voffB); PG8_STAGE(PG8_SA(0, 0), cA, voffA); PG8_STAGE(PG8_SA(0, 1), cA + hstep, voffA);
;         if (wr == 1) PG8_BAR;
;         PG8_WAIT_V(2); PG8_BAR;
;         PG8_STAGE(PG8_SB(1, 0), cB + kstep, voffB); PG8_STAGE(PG8_SA(1, 0), cA + kstep, voffA); PG8_STAGE(PG8_SB(1, 1), cB + hstep + kstep, voffB);
;         PG8_WAIT_V(6); PG8_BAR;
.LBB0_1216:
	s_add_u32 s14, s6, 0x1a600000
	s_addc_u32 s15, s7, 0
	s_add_u32 s16, s16, 0x217d4500
	s_addc_u32 s17, s17, 0
	s_add_u32 s18, s18, 0x238d4500
	s_addc_u32 s19, s19, 0
	s_add_i32 m0, s70, 0x18000
	v_lshl_add_u64 v[2:3], v[2:3], 0, s[52:53]
	global_load_lds_dwordx4 v[2:3], off
	v_lshl_add_u64 v[2:3], v[4:5], 0, s[52:53]
	s_add_i32 m0, s70, 0x1a000
	s_add_i32 s79, s70, 0x8000
	global_load_lds_dwordx4 v[2:3], off
	v_lshl_add_u64 v[2:3], v[10:11], 0, s[52:53]
	s_mov_b32 m0, s79
	s_add_i32 s82, s70, 0xa000
	global_load_lds_dwordx4 v[2:3], off
	v_lshl_add_u64 v[2:3], v[12:13], 0, s[52:53]
	s_mov_b32 m0, s82
	v_bfe_u32 v189, v14, 4, 2
	global_load_lds_dwordx4 v[2:3], off
	s_add_i32 m0, s70, 0x1c000
	v_lshl_add_u64 v[2:3], v[6:7], 0, s[52:53]
	global_load_lds_dwordx4 v[2:3], off
	v_lshl_add_u64 v[2:3], v[8:9], 0, s[52:53]
	s_add_i32 m0, s70, 0x1e000
	s_lshr_b32 s5, s5, 26
	global_load_lds_dwordx4 v[2:3], off
	s_waitcnt vmcnt(8)
	s_barrier
	v_and_b32_e32 v194, 15, v14
	s_add_i32 s5, s4, s5
	v_lshlrev_b32_e32 v2, 4, v189
	v_lshlrev_b32_e32 v3, 2, v14
	s_ashr_i32 s83, s5, 6
	v_lshl_or_b32 v2, v194, 6, v2
	s_lshl_b32 s5, s20, 13
	v_and_b32_e32 v3, 32, v3
	v_bitop3_b32 v4, v2, s5, v3 bitop3:0xde
	s_lshl_b32 s5, s21, 5
	s_and_b32 s85, s5, 0x60
	s_lshl_b32 s84, s20, 6
	s_lshl_b32 s5, s85, 7
	s_cmp_gt_i32 s4, 63
	v_bitop3_b32 v195, v2, s5, v3 bitop3:0xde
	s_cselect_b64 s[20:21], -1, 0
	s_add_i32 s86, s83, -2
	v_add_u32_e32 v2, v17, v15
	s_cmpk_lt_u32 s22, 0x100
	v_add_lshl_u32 v2, v2, v16, 1
	v_mov_b32_e32 v3, v1
	s_waitcnt vmcnt(6)
	s_cselect_b64 s[22:23], -1, 0
	s_ashr_i32 s87, s24, 31
	s_ashr_i32 s90, s25, 31
	v_lshl_add_u64 v[136:137], s[8:9], 0, v[2:3]
	v_add_u32_e32 v2, v20, v18
	s_add_u32 s28, s6, 0x1a708100
	v_add_lshl_u32 v2, v2, v19, 1
	s_addc_u32 s29, s7, 0
	v_lshl_add_u64 v[138:139], s[8:9], 0, v[2:3]
	s_mov_b32 s91, 0
	v_add_u32_e32 v196, 0, v4
	s_barrier
	s_branch .LBB0_1219

; #define PG8_STAGE(bufoff, gbase, voff) do { _Pragma("unroll") for (int _i = 0; _i < 2; ++_i) \
;         __builtin_amdgcn_global_load_lds((const unsigned*)((const char*)(gbase) + (voff)[_i]), (PG8_LAS unsigned*)(lds + (bufoff) + ldsw + _i * 8192), 16, 0, 0); } while (0)
; #define PG8_WAIT_V(n) asm volatile("s_waitcnt vmcnt(" #n ")" ::: "memory")
; #define PG8_BAR __builtin_amdgcn_s_barrier()
; template <class Epi, class Sched, bool ALIGN_EPI = false, bool SP2 = false>
; __device__ __forceinline__ void gemm_phase(PG8_LAS unsigned char* lds, const Gemm g, const Sched& S, const Epi& E) {
;     ...
;         PG8_STAGE(PG8_SB(0, 0), cB, voffB); PG8_STAGE(PG8_SB(0, 1), cB + hstep, voffB); PG8_STAGE(PG8_SA(0, 0), cA, voffA); PG8_STAGE(PG8_SA(0, 1), cA + hstep, voffA);
;         if (wr == 1) PG8_BAR;
;         PG8_WAIT_V(2); PG8_BAR;
;         PG8_STAGE(PG8_SB(1, 0), cB + kstep, voffB); PG8_STAGE(PG8_SA(1, 0), cA + kstep, voffA); PG8_STAGE(PG8_SB(1, 1), cB + hstep + kstep, voffB);
;         PG8_WAIT_V(6); PG8_BAR;
.LBB0_1452:
	s_add_u32 s18, s18, 0x2bcd4500
	s_addc_u32 s19, s19, 0
	s_add_u32 s20, s20, 0x384d4500
	s_addc_u32 s21, s21, 0
	s_add_u32 s22, s22, 0x2ddd4500
	s_addc_u32 s23, s23, 0
	s_add_u32 s28, s28, 0x31fd4500
	s_addc_u32 s29, s29, 0
	s_add_i32 m0, s79, 0x18000
	v_lshl_add_u64 v[2:3], v[2:3], 0, s[52:53]
	global_load_lds_dwordx4 v[2:3], off
	v_lshl_add_u64 v[2:3], v[4:5], 0, s[52:53]
	s_add_i32 m0, s79, 0x1a000
	s_add_i32 s85, s79, 0x8000
	global_load_lds_dwordx4 v[2:3], off
	v_lshl_add_u64 v[2:3], v[10:11], 0, s[52:53]
	s_mov_b32 m0, s85
	s_add_i32 s86, s79, 0xa000
	global_load_lds_dwordx4 v[2:3], off
	v_lshl_add_u64 v[2:3], v[12:13], 0, s[52:53]
	s_mov_b32 m0, s86
	v_bfe_u32 v189, v0, 4, 2
	global_load_lds_dwordx4 v[2:3], off
	s_add_i32 m0, s79, 0x1c000
	v_lshl_add_u64 v[2:3], v[6:7], 0, s[52:53]
	global_load_lds_dwordx4 v[2:3], off
	v_lshl_add_u64 v[2:3], v[8:9], 0, s[52:53]
	s_add_i32 m0, s79, 0x1e000
	s_lshr_b32 s5, s5, 26
	global_load_lds_dwordx4 v[2:3], off
	s_waitcnt vmcnt(8)
	s_barrier
	v_and_b32_e32 v212, 15, v0
	s_add_i32 s5, s4, s5
	v_lshlrev_b32_e32 v2, 4, v189
	v_lshlrev_b32_e32 v0, 2, v0
	s_ashr_i32 s87, s5, 6
	v_lshl_or_b32 v2, v212, 6, v2
	s_lshl_b32 s5, s30, 13
	v_and_b32_e32 v0, 32, v0
	v_bitop3_b32 v3, v2, s5, v0 bitop3:0xde
	s_lshl_b32 s5, s24, 5
	s_and_b32 s90, s5, 0x60
	s_lshl_b32 s5, s90, 7
	s_lshl_b32 s91, s30, 6
	v_bitop3_b32 v213, v2, s5, v0 bitop3:0xde
	v_add_u32_e32 v0, v19, v17
	s_cmp_gt_i32 s4, 63
	v_add_lshl_u32 v0, v0, v18, 1
	s_waitcnt vmcnt(6)
	s_cselect_b64 s[30:31], -1, 0
	s_add_i32 s24, s87, -2
	v_lshl_add_u64 v[150:151], s[12:13], 0, v[0:1]
	v_add_u32_e32 v0, v16, v14
	s_cmpk_lt_u32 s25, 0x100
	v_add_lshl_u32 v0, v0, v15, 1
	s_cselect_b64 s[92:93], -1, 0
	s_ashr_i32 s25, s91, 31
	v_lshl_add_u64 v[152:153], s[12:13], 0, v[0:1]
	s_mov_b32 s73, 0
	v_add_u32_e32 v214, 0, v3
	s_barrier
	s_branch .LBB0_1455

; #define PG8_STAGE(bufoff, gbase, voff) do { _Pragma("unroll") for (int _i = 0; _i < 2; ++_i) \
;         __builtin_amdgcn_global_load_lds((const unsigned*)((const char*)(gbase) + (voff)[_i]), (PG8_LAS unsigned*)(lds + (bufoff) + ldsw + _i * 8192), 16, 0, 0); } while (0)
; #define PG8_WAIT_V(n) asm volatile("s_waitcnt vmcnt(" #n ")" ::: "memory")
; #define PG8_BAR __builtin_amdgcn_s_barrier()
; template <class Epi, class Sched, bool ALIGN_EPI = false, bool SP2 = false>
; __device__ __forceinline__ void gemm_phase(PG8_LAS unsigned char* lds, const Gemm g, const Sched& S, const Epi& E) {
;     ...
;         PG8_STAGE(PG8_SB(0, 0), cB, voffB); PG8_STAGE(PG8_SB(0, 1), cB + hstep, voffB); PG8_STAGE(PG8_SA(0, 0), cA, voffA); PG8_STAGE(PG8_SA(0, 1), cA + hstep, voffA);
;         if (wr == 1) PG8_BAR;
;         PG8_WAIT_V(2); PG8_BAR;
;         PG8_STAGE(PG8_SB(1, 0), cB + kstep, voffB); PG8_STAGE(PG8_SA(1, 0), cA + kstep, voffA); PG8_STAGE(PG8_SB(1, 1), cB + hstep + kstep, voffB);
;         PG8_WAIT_V(6); PG8_BAR;
.LBB0_1834:
	s_add_u32 s14, s6, 0x1a600000
	s_addc_u32 s15, s7, 0
	s_add_u32 s16, s16, 0x1bd14500
	s_addc_u32 s17, s17, 0
	s_add_i32 m0, s56, 0x18000
	v_lshl_add_u64 v[2:3], v[2:3], 0, s[52:53]
	global_load_lds_dwordx4 v[2:3], off
	v_lshl_add_u64 v[2:3], v[4:5], 0, s[52:53]
	s_add_i32 m0, s56, 0x1a000
	s_add_i32 s68, s56, 0x8000
	global_load_lds_dwordx4 v[2:3], off
	v_lshl_add_u64 v[2:3], v[10:11], 0, s[52:53]
	s_mov_b32 m0, s68
	s_add_i32 s69, s56, 0xa000
	global_load_lds_dwordx4 v[2:3], off
	v_lshl_add_u64 v[2:3], v[12:13], 0, s[52:53]
	s_mov_b32 m0, s69
	v_bfe_u32 v159, v14, 4, 2
	global_load_lds_dwordx4 v[2:3], off
	s_add_i32 m0, s56, 0x1c000
	v_lshl_add_u64 v[2:3], v[6:7], 0, s[52:53]
	global_load_lds_dwordx4 v[2:3], off
	v_lshl_add_u64 v[2:3], v[8:9], 0, s[52:53]
	s_add_i32 m0, s56, 0x1e000
	s_lshr_b32 s5, s5, 26
	global_load_lds_dwordx4 v[2:3], off
	s_waitcnt vmcnt(8)
	s_barrier
	v_and_b32_e32 v161, 15, v14
	s_add_i32 s5, s4, s5
	v_lshlrev_b32_e32 v2, 4, v159
	v_lshlrev_b32_e32 v3, 2, v14
	s_ashr_i32 s70, s5, 6
	v_lshl_or_b32 v2, v161, 6, v2
	s_lshl_b32 s5, s19, 13
	v_and_b32_e32 v3, 32, v3
	v_bitop3_b32 v4, v2, s5, v3 bitop3:0xde
	s_lshl_b32 s5, s21, 5
	s_and_b32 s5, s5, 0x60
	s_sext_i32_i16 s82, s18
	s_lshl_b32 s71, s19, 6
	s_lshl_b32 s18, s5, 7
	v_bitop3_b32 v163, v2, s18, v3 bitop3:0xde
	s_cmp_gt_i32 s4, 63
	v_add_u32_e32 v2, v17, v15
	s_cselect_b64 s[18:19], -1, 0
	s_add_i32 s73, s70, -2
	v_add_lshl_u32 v2, v2, v16, 1
	v_mov_b32_e32 v3, v1
	s_waitcnt vmcnt(6)
	s_cmpk_lt_u32 s20, 0x100
	v_lshl_add_u64 v[136:137], s[8:9], 0, v[2:3]
	v_add_u32_e32 v2, v20, v18
	s_cselect_b64 s[20:21], -1, 0
	s_add_u32 s22, s6, 0x1a708100
	v_add_lshl_u32 v2, v2, v19, 1
	s_addc_u32 s23, s7, 0
	s_ashr_i32 s75, s2, 31
	v_lshl_add_u64 v[138:139], s[8:9], 0, v[2:3]
	s_mov_b32 s78, 0
	v_add_u32_e32 v165, 0, v4
	s_lshl_b32 s48, s5, 1
	s_barrier
	s_branch .LBB0_1837

; #define PG8_STAGE(bufoff, gbase, voff) do { _Pragma("unroll") for (int _i = 0; _i < 2; ++_i) \
;         __builtin_amdgcn_global_load_lds((const unsigned*)((const char*)(gbase) + (voff)[_i]), (PG8_LAS unsigned*)(lds + (bufoff) + ldsw + _i * 8192), 16, 0, 0); } while (0)
; #define PG8_WAIT_V(n) asm volatile("s_waitcnt vmcnt(" #n ")" ::: "memory")
; #define PG8_BAR __builtin_amdgcn_s_barrier()
; template <class Epi, class Sched, bool ALIGN_EPI = false, bool SP2 = false>
; __device__ __forceinline__ void gemm_phase(PG8_LAS unsigned char* lds, const Gemm g, const Sched& S, const Epi& E) {
;     ...
;         PG8_STAGE(PG8_SB(0, 0), cB, voffB); PG8_STAGE(PG8_SB(0, 1), cB + hstep, voffB); PG8_STAGE(PG8_SA(0, 0), cA, voffA); PG8_STAGE(PG8_SA(0, 1), cA + hstep, voffA);
;         if (wr == 1) PG8_BAR;
;         PG8_WAIT_V(2); PG8_BAR;
;         PG8_STAGE(PG8_SB(1, 0), cB + kstep, voffB); PG8_STAGE(PG8_SA(1, 0), cA + kstep, voffA); PG8_STAGE(PG8_SB(1, 1), cB + hstep + kstep, voffB);
;         PG8_WAIT_V(6); PG8_BAR;
.LBB0_1940:
	s_add_u32 s14, s14, 0x14300000
	s_addc_u32 s15, s15, 0
	s_add_u32 s16, s16, 0x18500000
	s_addc_u32 s17, s17, 0
	s_add_u32 s66, s18, 0x1a600000
	s_addc_u32 s67, s19, 0
	s_add_i32 m0, s56, 0x18000
	v_lshl_add_u64 v[2:3], v[2:3], 0, s[52:53]
	global_load_lds_dwordx4 v[2:3], off
	v_lshl_add_u64 v[2:3], v[4:5], 0, s[52:53]
	s_add_i32 m0, s56, 0x1a000
	s_add_i32 s68, s56, 0x8000
	global_load_lds_dwordx4 v[2:3], off
	v_lshl_add_u64 v[2:3], v[10:11], 0, s[52:53]
	s_mov_b32 m0, s68
	s_add_i32 s69, s56, 0xa000
	global_load_lds_dwordx4 v[2:3], off
	v_lshl_add_u64 v[2:3], v[12:13], 0, s[52:53]
	s_mov_b32 m0, s69
	v_bfe_u32 v189, v14, 4, 2
	global_load_lds_dwordx4 v[2:3], off
	s_add_i32 m0, s56, 0x1c000
	v_lshl_add_u64 v[2:3], v[6:7], 0, s[52:53]
	global_load_lds_dwordx4 v[2:3], off
	v_lshl_add_u64 v[2:3], v[8:9], 0, s[52:53]
	s_add_i32 m0, s56, 0x1e000
	s_lshr_b32 s7, s7, 26
	global_load_lds_dwordx4 v[2:3], off
	s_waitcnt vmcnt(8)
	s_barrier
	v_and_b32_e32 v233, 15, v14
	s_add_i32 s7, s6, s7
	v_lshlrev_b32_e32 v2, 4, v189
	v_lshlrev_b32_e32 v3, 2, v14
	s_and_b32 s70, s20, 3
	s_ashr_i32 s71, s7, 6
	v_lshl_or_b32 v2, v233, 6, v2
	s_lshl_b32 s7, s21, 13
	v_and_b32_e32 v3, 32, v3
	s_lshl_b32 s73, s21, 6
	v_bitop3_b32 v4, v2, s7, v3 bitop3:0xde
	s_lshl_b32 s48, s70, 5
	s_lshl_b32 s7, s70, 12
	s_cmp_gt_i32 s6, 63
	s_cselect_b64 s[18:19], -1, 0
	s_add_i32 s75, s71, -2
	s_cmpk_lt_u32 s22, 0x100
	v_bitop3_b32 v234, v2, s7, v3 bitop3:0xde
	s_cselect_b64 s[20:21], -1, 0
	s_ashr_i32 s78, s24, 31
	s_ashr_i32 s79, s2, 31
	s_lshl_b32 s6, s70, 7
	v_add_u32_e32 v2, v17, v15
	s_add_u32 s4, s4, s6
	v_add_lshl_u32 v2, v2, v16, 1
	v_mov_b32_e32 v3, v1
	s_waitcnt vmcnt(6)
	s_addc_u32 s5, s5, 0
	v_lshl_add_u64 v[136:137], s[8:9], 0, v[2:3]
	v_add_u32_e32 v2, v20, v18
	s_add_u32 s81, s4, 0x14300000
	v_add_lshl_u32 v2, v2, v19, 1
	s_addc_u32 s82, s5, 0
	v_lshl_add_u64 v[138:139], s[8:9], 0, v[2:3]
	s_mov_b32 s83, 0
	v_add_u32_e32 v235, 0, v4
	s_barrier
	s_branch .LBB0_1943
